# GLA gate (softplus) epilogue blocks rewritten with packed f32 math and batched exp/log: 72 instead of 286 instructions per 8 elements
# speedup vs baseline: 1.0073x; 1.0073x over previous
.LBB0_656:
	s_nop 1
	v_lshlrev_b64 v[152:153], 10, v[174:175]
	s_and_b64 vcc, exec, s[0:1]
	v_lshl_add_u64 v[186:187], s[8:9], 0, v[152:153]
	v_lshlrev_b32_e32 v172, 2, v196
	s_cbranch_vccz .LBB0_658
	s_waitcnt vmcnt(0)
	s_mov_b32 s0, 0x3f317217
	s_mov_b32 s2, 0x3d800000
	s_mov_b32 s6, 0x3377d1cf
	s_mov_b32 s98, 1.0
	v_mov_b32_e32 v173, v177
	v_pk_add_f32 v[148:149], v[148:149], v[218:219]
	v_pk_add_f32 v[150:151], v[150:151], v[220:221]
	v_pk_add_f32 v[144:145], v[144:145], v[214:215]
	v_pk_add_f32 v[146:147], v[146:147], v[216:217]
	v_min_f32_e32 v230, 0, v148
	v_min_f32_e32 v231, 0, v149
	v_min_f32_e32 v232, 0, v150
	v_min_f32_e32 v233, 0, v151
	v_min_f32_e32 v234, 0, v144
	v_min_f32_e32 v235, 0, v145
	v_min_f32_e32 v236, 0, v146
	v_min_f32_e32 v237, 0, v147
	v_mul_f32_e64 v148, |v148|, s70
	v_mul_f32_e64 v149, |v149|, s70
	v_mul_f32_e64 v150, |v150|, s70
	v_mul_f32_e64 v151, |v151|, s70
	v_mul_f32_e64 v144, |v144|, s70
	v_mul_f32_e64 v145, |v145|, s70
	v_mul_f32_e64 v146, |v146|, s70
	v_mul_f32_e64 v147, |v147|, s70
	v_exp_f32_e32 v148, v148
	v_exp_f32_e32 v149, v149
	v_exp_f32_e32 v150, v150
	v_exp_f32_e32 v151, v151
	v_exp_f32_e32 v144, v144
	v_exp_f32_e32 v145, v145
	v_exp_f32_e32 v146, v146
	v_exp_f32_e32 v147, v147
	v_pk_add_f32 v[148:149], v[148:149], s[98:99] op_sel_hi:[1,0]
	v_pk_add_f32 v[150:151], v[150:151], s[98:99] op_sel_hi:[1,0]
	v_pk_add_f32 v[144:145], v[144:145], s[98:99] op_sel_hi:[1,0]
	v_pk_add_f32 v[146:147], v[146:147], s[98:99] op_sel_hi:[1,0]
	v_log_f32_e32 v148, v148
	v_log_f32_e32 v149, v149
	v_log_f32_e32 v150, v150
	v_log_f32_e32 v151, v151
	v_log_f32_e32 v144, v144
	v_log_f32_e32 v145, v145
	v_log_f32_e32 v146, v146
	v_log_f32_e32 v147, v147
	v_lshl_add_u64 v[152:153], v[186:187], 0, v[172:173]
	v_pk_mul_f32 v[238:239], v[148:149], s[0:1] op_sel_hi:[1,0]
	v_pk_mul_f32 v[240:241], v[150:151], s[0:1] op_sel_hi:[1,0]
	v_pk_mul_f32 v[242:243], v[144:145], s[0:1] op_sel_hi:[1,0]
	v_pk_mul_f32 v[244:245], v[146:147], s[0:1] op_sel_hi:[1,0]
	v_pk_fma_f32 v[238:239], v[148:149], s[0:1], v[238:239] op_sel_hi:[1,0,1] neg_lo:[0,0,1] neg_hi:[0,0,1]
	v_pk_fma_f32 v[240:241], v[150:151], s[0:1], v[240:241] op_sel_hi:[1,0,1] neg_lo:[0,0,1] neg_hi:[0,0,1]
	v_pk_fma_f32 v[242:243], v[144:145], s[0:1], v[242:243] op_sel_hi:[1,0,1] neg_lo:[0,0,1] neg_hi:[0,0,1]
	v_pk_fma_f32 v[244:245], v[146:147], s[0:1], v[244:245] op_sel_hi:[1,0,1] neg_lo:[0,0,1] neg_hi:[0,0,1]
	v_pk_fma_f32 v[238:239], v[148:149], s[6:7], v[238:239] op_sel_hi:[1,0,1]
	v_pk_fma_f32 v[240:241], v[150:151], s[6:7], v[240:241] op_sel_hi:[1,0,1]
	v_pk_fma_f32 v[242:243], v[144:145], s[6:7], v[242:243] op_sel_hi:[1,0,1]
	v_pk_fma_f32 v[244:245], v[146:147], s[6:7], v[244:245] op_sel_hi:[1,0,1]
	v_pk_fma_f32 v[238:239], v[148:149], s[0:1], v[238:239] op_sel_hi:[1,0,1]
	v_pk_fma_f32 v[240:241], v[150:151], s[0:1], v[240:241] op_sel_hi:[1,0,1]
	v_pk_fma_f32 v[242:243], v[144:145], s[0:1], v[242:243] op_sel_hi:[1,0,1]
	v_pk_fma_f32 v[244:245], v[146:147], s[0:1], v[244:245] op_sel_hi:[1,0,1]
	v_pk_add_f32 v[148:149], v[230:231], v[238:239] neg_lo:[0,1] neg_hi:[0,1]
	v_pk_add_f32 v[150:151], v[232:233], v[240:241] neg_lo:[0,1] neg_hi:[0,1]
	v_pk_add_f32 v[144:145], v[234:235], v[242:243] neg_lo:[0,1] neg_hi:[0,1]
	v_pk_add_f32 v[146:147], v[236:237], v[244:245] neg_lo:[0,1] neg_hi:[0,1]
	v_pk_mul_f32 v[148:149], v[148:149], s[2:3] op_sel_hi:[1,0]
	v_pk_mul_f32 v[150:151], v[150:151], s[2:3] op_sel_hi:[1,0]
	v_pk_mul_f32 v[144:145], v[144:145], s[2:3] op_sel_hi:[1,0]
	v_pk_mul_f32 v[146:147], v[146:147], s[2:3] op_sel_hi:[1,0]
	s_mov_b32 s0, 0x7f800000
	s_mov_b64 s[6:7], exec
	s_mov_b64 vcc, 0
	global_store_dwordx4 v[152:153], v[148:151], off
	global_store_dwordx4 v[152:153], v[144:147], off offset:16

.LBB0_671:
	s_and_b64 vcc, exec, s[0:1]
	s_cbranch_vccz .LBB0_673
	s_mov_b32 s0, 0x3f317217
	s_mov_b32 s2, 0x3d800000
	s_mov_b32 s6, 0x3377d1cf
	s_mov_b32 s98, 1.0
	v_mov_b32_e32 v173, v177
	v_pk_add_f32 v[140:141], v[140:141], v[226:227]
	v_pk_add_f32 v[142:143], v[142:143], v[228:229]
	v_pk_add_f32 v[136:137], v[136:137], v[222:223]
	v_pk_add_f32 v[138:139], v[138:139], v[224:225]
	v_min_f32_e32 v230, 0, v140
	v_min_f32_e32 v231, 0, v141
	v_min_f32_e32 v232, 0, v142
	v_min_f32_e32 v233, 0, v143
	v_min_f32_e32 v234, 0, v136
	v_min_f32_e32 v235, 0, v137
	v_min_f32_e32 v236, 0, v138
	v_min_f32_e32 v237, 0, v139
	v_mul_f32_e64 v140, |v140|, s70
	v_mul_f32_e64 v141, |v141|, s70
	v_mul_f32_e64 v142, |v142|, s70
	v_mul_f32_e64 v143, |v143|, s70
	v_mul_f32_e64 v136, |v136|, s70
	v_mul_f32_e64 v137, |v137|, s70
	v_mul_f32_e64 v138, |v138|, s70
	v_mul_f32_e64 v139, |v139|, s70
	v_exp_f32_e32 v140, v140
	v_exp_f32_e32 v141, v141
	v_exp_f32_e32 v142, v142
	v_exp_f32_e32 v143, v143
	v_exp_f32_e32 v136, v136
	v_exp_f32_e32 v137, v137
	v_exp_f32_e32 v138, v138
	v_exp_f32_e32 v139, v139
	v_pk_add_f32 v[140:141], v[140:141], s[98:99] op_sel_hi:[1,0]
	v_pk_add_f32 v[142:143], v[142:143], s[98:99] op_sel_hi:[1,0]
	v_pk_add_f32 v[136:137], v[136:137], s[98:99] op_sel_hi:[1,0]
	v_pk_add_f32 v[138:139], v[138:139], s[98:99] op_sel_hi:[1,0]
	v_log_f32_e32 v140, v140
	v_log_f32_e32 v141, v141
	v_log_f32_e32 v142, v142
	v_log_f32_e32 v143, v143
	v_log_f32_e32 v136, v136
	v_log_f32_e32 v137, v137
	v_log_f32_e32 v138, v138
	v_log_f32_e32 v139, v139
	v_lshl_add_u64 v[144:145], v[186:187], 0, v[172:173]
	v_pk_mul_f32 v[238:239], v[140:141], s[0:1] op_sel_hi:[1,0]
	v_pk_mul_f32 v[240:241], v[142:143], s[0:1] op_sel_hi:[1,0]
	v_pk_mul_f32 v[242:243], v[136:137], s[0:1] op_sel_hi:[1,0]
	v_pk_mul_f32 v[244:245], v[138:139], s[0:1] op_sel_hi:[1,0]
	v_pk_fma_f32 v[238:239], v[140:141], s[0:1], v[238:239] op_sel_hi:[1,0,1] neg_lo:[0,0,1] neg_hi:[0,0,1]
	v_pk_fma_f32 v[240:241], v[142:143], s[0:1], v[240:241] op_sel_hi:[1,0,1] neg_lo:[0,0,1] neg_hi:[0,0,1]
	v_pk_fma_f32 v[242:243], v[136:137], s[0:1], v[242:243] op_sel_hi:[1,0,1] neg_lo:[0,0,1] neg_hi:[0,0,1]
	v_pk_fma_f32 v[244:245], v[138:139], s[0:1], v[244:245] op_sel_hi:[1,0,1] neg_lo:[0,0,1] neg_hi:[0,0,1]
	v_pk_fma_f32 v[238:239], v[140:141], s[6:7], v[238:239] op_sel_hi:[1,0,1]
	v_pk_fma_f32 v[240:241], v[142:143], s[6:7], v[240:241] op_sel_hi:[1,0,1]
	v_pk_fma_f32 v[242:243], v[136:137], s[6:7], v[242:243] op_sel_hi:[1,0,1]
	v_pk_fma_f32 v[244:245], v[138:139], s[6:7], v[244:245] op_sel_hi:[1,0,1]
	v_pk_fma_f32 v[238:239], v[140:141], s[0:1], v[238:239] op_sel_hi:[1,0,1]
	v_pk_fma_f32 v[240:241], v[142:143], s[0:1], v[240:241] op_sel_hi:[1,0,1]
	v_pk_fma_f32 v[242:243], v[136:137], s[0:1], v[242:243] op_sel_hi:[1,0,1]
	v_pk_fma_f32 v[244:245], v[138:139], s[0:1], v[244:245] op_sel_hi:[1,0,1]
	v_pk_add_f32 v[140:141], v[230:231], v[238:239] neg_lo:[0,1] neg_hi:[0,1]
	v_pk_add_f32 v[142:143], v[232:233], v[240:241] neg_lo:[0,1] neg_hi:[0,1]
	v_pk_add_f32 v[136:137], v[234:235], v[242:243] neg_lo:[0,1] neg_hi:[0,1]
	v_pk_add_f32 v[138:139], v[236:237], v[244:245] neg_lo:[0,1] neg_hi:[0,1]
	v_pk_mul_f32 v[140:141], v[140:141], s[2:3] op_sel_hi:[1,0]
	v_pk_mul_f32 v[142:143], v[142:143], s[2:3] op_sel_hi:[1,0]
	v_pk_mul_f32 v[136:137], v[136:137], s[2:3] op_sel_hi:[1,0]
	v_pk_mul_f32 v[138:139], v[138:139], s[2:3] op_sel_hi:[1,0]
	s_mov_b32 s0, 0x7f800000
	s_mov_b64 s[6:7], exec
	s_mov_b64 vcc, 0
	global_store_dwordx4 v[144:145], v[140:143], off offset:512
	global_store_dwordx4 v[144:145], v[136:139], off offset:528

.LBB0_696:
	s_nop 1
	v_lshlrev_b64 v[136:137], 10, v[144:145]
	s_and_b64 vcc, exec, s[0:1]
	v_lshl_add_u64 v[144:145], s[8:9], 0, v[136:137]
	s_cbranch_vccz .LBB0_698
	s_mov_b32 s0, 0x3f317217
	s_mov_b32 s2, 0x3d800000
	s_mov_b32 s6, 0x3377d1cf
	s_mov_b32 s98, 1.0
	v_mov_b32_e32 v173, v177
	v_pk_add_f32 v[132:133], v[132:133], v[218:219]
	v_pk_add_f32 v[134:135], v[134:135], v[220:221]
	v_pk_add_f32 v[128:129], v[128:129], v[214:215]
	v_pk_add_f32 v[130:131], v[130:131], v[216:217]
	v_min_f32_e32 v230, 0, v132
	v_min_f32_e32 v231, 0, v133
	v_min_f32_e32 v232, 0, v134
	v_min_f32_e32 v233, 0, v135
	v_min_f32_e32 v234, 0, v128
	v_min_f32_e32 v235, 0, v129
	v_min_f32_e32 v236, 0, v130
	v_min_f32_e32 v237, 0, v131
	v_mul_f32_e64 v132, |v132|, s70
	v_mul_f32_e64 v133, |v133|, s70
	v_mul_f32_e64 v134, |v134|, s70
	v_mul_f32_e64 v135, |v135|, s70
	v_mul_f32_e64 v128, |v128|, s70
	v_mul_f32_e64 v129, |v129|, s70
	v_mul_f32_e64 v130, |v130|, s70
	v_mul_f32_e64 v131, |v131|, s70
	v_exp_f32_e32 v132, v132
	v_exp_f32_e32 v133, v133
	v_exp_f32_e32 v134, v134
	v_exp_f32_e32 v135, v135
	v_exp_f32_e32 v128, v128
	v_exp_f32_e32 v129, v129
	v_exp_f32_e32 v130, v130
	v_exp_f32_e32 v131, v131
	v_pk_add_f32 v[132:133], v[132:133], s[98:99] op_sel_hi:[1,0]
	v_pk_add_f32 v[134:135], v[134:135], s[98:99] op_sel_hi:[1,0]
	v_pk_add_f32 v[128:129], v[128:129], s[98:99] op_sel_hi:[1,0]
	v_pk_add_f32 v[130:131], v[130:131], s[98:99] op_sel_hi:[1,0]
	v_log_f32_e32 v132, v132
	v_log_f32_e32 v133, v133
	v_log_f32_e32 v134, v134
	v_log_f32_e32 v135, v135
	v_log_f32_e32 v128, v128
	v_log_f32_e32 v129, v129
	v_log_f32_e32 v130, v130
	v_log_f32_e32 v131, v131
	v_lshl_add_u64 v[136:137], v[144:145], 0, v[172:173]
	v_pk_mul_f32 v[238:239], v[132:133], s[0:1] op_sel_hi:[1,0]
	v_pk_mul_f32 v[240:241], v[134:135], s[0:1] op_sel_hi:[1,0]
	v_pk_mul_f32 v[242:243], v[128:129], s[0:1] op_sel_hi:[1,0]
	v_pk_mul_f32 v[244:245], v[130:131], s[0:1] op_sel_hi:[1,0]
	v_pk_fma_f32 v[238:239], v[132:133], s[0:1], v[238:239] op_sel_hi:[1,0,1] neg_lo:[0,0,1] neg_hi:[0,0,1]
	v_pk_fma_f32 v[240:241], v[134:135], s[0:1], v[240:241] op_sel_hi:[1,0,1] neg_lo:[0,0,1] neg_hi:[0,0,1]
	v_pk_fma_f32 v[242:243], v[128:129], s[0:1], v[242:243] op_sel_hi:[1,0,1] neg_lo:[0,0,1] neg_hi:[0,0,1]
	v_pk_fma_f32 v[244:245], v[130:131], s[0:1], v[244:245] op_sel_hi:[1,0,1] neg_lo:[0,0,1] neg_hi:[0,0,1]
	v_pk_fma_f32 v[238:239], v[132:133], s[6:7], v[238:239] op_sel_hi:[1,0,1]
	v_pk_fma_f32 v[240:241], v[134:135], s[6:7], v[240:241] op_sel_hi:[1,0,1]
	v_pk_fma_f32 v[242:243], v[128:129], s[6:7], v[242:243] op_sel_hi:[1,0,1]
	v_pk_fma_f32 v[244:245], v[130:131], s[6:7], v[244:245] op_sel_hi:[1,0,1]
	v_pk_fma_f32 v[238:239], v[132:133], s[0:1], v[238:239] op_sel_hi:[1,0,1]
	v_pk_fma_f32 v[240:241], v[134:135], s[0:1], v[240:241] op_sel_hi:[1,0,1]
	v_pk_fma_f32 v[242:243], v[128:129], s[0:1], v[242:243] op_sel_hi:[1,0,1]
	v_pk_fma_f32 v[244:245], v[130:131], s[0:1], v[244:245] op_sel_hi:[1,0,1]
	v_pk_add_f32 v[132:133], v[230:231], v[238:239] neg_lo:[0,1] neg_hi:[0,1]
	v_pk_add_f32 v[134:135], v[232:233], v[240:241] neg_lo:[0,1] neg_hi:[0,1]
	v_pk_add_f32 v[128:129], v[234:235], v[242:243] neg_lo:[0,1] neg_hi:[0,1]
	v_pk_add_f32 v[130:131], v[236:237], v[244:245] neg_lo:[0,1] neg_hi:[0,1]
	v_pk_mul_f32 v[132:133], v[132:133], s[2:3] op_sel_hi:[1,0]
	v_pk_mul_f32 v[134:135], v[134:135], s[2:3] op_sel_hi:[1,0]
	v_pk_mul_f32 v[128:129], v[128:129], s[2:3] op_sel_hi:[1,0]
	v_pk_mul_f32 v[130:131], v[130:131], s[2:3] op_sel_hi:[1,0]
	s_mov_b32 s0, 0x7f800000
	s_mov_b64 s[6:7], exec
	s_mov_b64 vcc, 0
	global_store_dwordx4 v[136:137], v[132:135], off
	global_store_dwordx4 v[136:137], v[128:131], off offset:16

.LBB0_711:
	s_and_b64 vcc, exec, s[0:1]
	s_cbranch_vccz .LBB0_713
	s_mov_b32 s0, 0x3f317217
	s_mov_b32 s2, 0x3d800000
	s_mov_b32 s6, 0x3377d1cf
	s_mov_b32 s98, 1.0
	v_mov_b32_e32 v173, v177
	v_pk_add_f32 v[124:125], v[124:125], v[226:227]
	v_pk_add_f32 v[126:127], v[126:127], v[228:229]
	v_pk_add_f32 v[120:121], v[120:121], v[222:223]
	v_pk_add_f32 v[122:123], v[122:123], v[224:225]
	v_min_f32_e32 v230, 0, v124
	v_min_f32_e32 v231, 0, v125
	v_min_f32_e32 v232, 0, v126
	v_min_f32_e32 v233, 0, v127
	v_min_f32_e32 v234, 0, v120
	v_min_f32_e32 v235, 0, v121
	v_min_f32_e32 v236, 0, v122
	v_min_f32_e32 v237, 0, v123
	v_mul_f32_e64 v124, |v124|, s70
	v_mul_f32_e64 v125, |v125|, s70
	v_mul_f32_e64 v126, |v126|, s70
	v_mul_f32_e64 v127, |v127|, s70
	v_mul_f32_e64 v120, |v120|, s70
	v_mul_f32_e64 v121, |v121|, s70
	v_mul_f32_e64 v122, |v122|, s70
	v_mul_f32_e64 v123, |v123|, s70
	v_exp_f32_e32 v124, v124
	v_exp_f32_e32 v125, v125
	v_exp_f32_e32 v126, v126
	v_exp_f32_e32 v127, v127
	v_exp_f32_e32 v120, v120
	v_exp_f32_e32 v121, v121
	v_exp_f32_e32 v122, v122
	v_exp_f32_e32 v123, v123
	v_pk_add_f32 v[124:125], v[124:125], s[98:99] op_sel_hi:[1,0]
	v_pk_add_f32 v[126:127], v[126:127], s[98:99] op_sel_hi:[1,0]
	v_pk_add_f32 v[120:121], v[120:121], s[98:99] op_sel_hi:[1,0]
	v_pk_add_f32 v[122:123], v[122:123], s[98:99] op_sel_hi:[1,0]
	v_log_f32_e32 v124, v124
	v_log_f32_e32 v125, v125
	v_log_f32_e32 v126, v126
	v_log_f32_e32 v127, v127
	v_log_f32_e32 v120, v120
	v_log_f32_e32 v121, v121
	v_log_f32_e32 v122, v122
	v_log_f32_e32 v123, v123
	v_lshl_add_u64 v[128:129], v[144:145], 0, v[172:173]
	v_pk_mul_f32 v[238:239], v[124:125], s[0:1] op_sel_hi:[1,0]
	v_pk_mul_f32 v[240:241], v[126:127], s[0:1] op_sel_hi:[1,0]
	v_pk_mul_f32 v[242:243], v[120:121], s[0:1] op_sel_hi:[1,0]
	v_pk_mul_f32 v[244:245], v[122:123], s[0:1] op_sel_hi:[1,0]
	v_pk_fma_f32 v[238:239], v[124:125], s[0:1], v[238:239] op_sel_hi:[1,0,1] neg_lo:[0,0,1] neg_hi:[0,0,1]
	v_pk_fma_f32 v[240:241], v[126:127], s[0:1], v[240:241] op_sel_hi:[1,0,1] neg_lo:[0,0,1] neg_hi:[0,0,1]
	v_pk_fma_f32 v[242:243], v[120:121], s[0:1], v[242:243] op_sel_hi:[1,0,1] neg_lo:[0,0,1] neg_hi:[0,0,1]
	v_pk_fma_f32 v[244:245], v[122:123], s[0:1], v[244:245] op_sel_hi:[1,0,1] neg_lo:[0,0,1] neg_hi:[0,0,1]
	v_pk_fma_f32 v[238:239], v[124:125], s[6:7], v[238:239] op_sel_hi:[1,0,1]
	v_pk_fma_f32 v[240:241], v[126:127], s[6:7], v[240:241] op_sel_hi:[1,0,1]
	v_pk_fma_f32 v[242:243], v[120:121], s[6:7], v[242:243] op_sel_hi:[1,0,1]
	v_pk_fma_f32 v[244:245], v[122:123], s[6:7], v[244:245] op_sel_hi:[1,0,1]
	v_pk_fma_f32 v[238:239], v[124:125], s[0:1], v[238:239] op_sel_hi:[1,0,1]
	v_pk_fma_f32 v[240:241], v[126:127], s[0:1], v[240:241] op_sel_hi:[1,0,1]
	v_pk_fma_f32 v[242:243], v[120:121], s[0:1], v[242:243] op_sel_hi:[1,0,1]
	v_pk_fma_f32 v[244:245], v[122:123], s[0:1], v[244:245] op_sel_hi:[1,0,1]
	v_pk_add_f32 v[124:125], v[230:231], v[238:239] neg_lo:[0,1] neg_hi:[0,1]
	v_pk_add_f32 v[126:127], v[232:233], v[240:241] neg_lo:[0,1] neg_hi:[0,1]
	v_pk_add_f32 v[120:121], v[234:235], v[242:243] neg_lo:[0,1] neg_hi:[0,1]
	v_pk_add_f32 v[122:123], v[236:237], v[244:245] neg_lo:[0,1] neg_hi:[0,1]
	v_pk_mul_f32 v[124:125], v[124:125], s[2:3] op_sel_hi:[1,0]
	v_pk_mul_f32 v[126:127], v[126:127], s[2:3] op_sel_hi:[1,0]
	v_pk_mul_f32 v[120:121], v[120:121], s[2:3] op_sel_hi:[1,0]
	v_pk_mul_f32 v[122:123], v[122:123], s[2:3] op_sel_hi:[1,0]
	s_mov_b32 s0, 0x7f800000
	s_mov_b64 s[6:7], exec
	s_mov_b64 vcc, 0
	global_store_dwordx4 v[128:129], v[124:127], off offset:512
	global_store_dwordx4 v[128:129], v[120:123], off offset:528

.LBB0_736:
	s_nop 1
	v_lshlrev_b64 v[112:113], 10, v[122:123]
	s_and_b64 vcc, exec, s[0:1]
	v_lshl_add_u64 v[122:123], s[8:9], 0, v[112:113]
	s_cbranch_vccz .LBB0_738
	s_mov_b32 s0, 0x3f317217
	s_mov_b32 s2, 0x3d800000
	s_mov_b32 s6, 0x3377d1cf
	s_mov_b32 s98, 1.0
	v_mov_b32_e32 v173, v177
	v_pk_add_f32 v[108:109], v[108:109], v[218:219]
	v_pk_add_f32 v[110:111], v[110:111], v[220:221]
	v_pk_add_f32 v[104:105], v[104:105], v[214:215]
	v_pk_add_f32 v[106:107], v[106:107], v[216:217]
	v_min_f32_e32 v230, 0, v108
	v_min_f32_e32 v231, 0, v109
	v_min_f32_e32 v232, 0, v110
	v_min_f32_e32 v233, 0, v111
	v_min_f32_e32 v234, 0, v104
	v_min_f32_e32 v235, 0, v105
	v_min_f32_e32 v236, 0, v106
	v_min_f32_e32 v237, 0, v107
	v_mul_f32_e64 v108, |v108|, s70
	v_mul_f32_e64 v109, |v109|, s70
	v_mul_f32_e64 v110, |v110|, s70
	v_mul_f32_e64 v111, |v111|, s70
	v_mul_f32_e64 v104, |v104|, s70
	v_mul_f32_e64 v105, |v105|, s70
	v_mul_f32_e64 v106, |v106|, s70
	v_mul_f32_e64 v107, |v107|, s70
	v_exp_f32_e32 v108, v108
	v_exp_f32_e32 v109, v109
	v_exp_f32_e32 v110, v110
	v_exp_f32_e32 v111, v111
	v_exp_f32_e32 v104, v104
	v_exp_f32_e32 v105, v105
	v_exp_f32_e32 v106, v106
	v_exp_f32_e32 v107, v107
	v_pk_add_f32 v[108:109], v[108:109], s[98:99] op_sel_hi:[1,0]
	v_pk_add_f32 v[110:111], v[110:111], s[98:99] op_sel_hi:[1,0]
	v_pk_add_f32 v[104:105], v[104:105], s[98:99] op_sel_hi:[1,0]
	v_pk_add_f32 v[106:107], v[106:107], s[98:99] op_sel_hi:[1,0]
	v_log_f32_e32 v108, v108
	v_log_f32_e32 v109, v109
	v_log_f32_e32 v110, v110
	v_log_f32_e32 v111, v111
	v_log_f32_e32 v104, v104
	v_log_f32_e32 v105, v105
	v_log_f32_e32 v106, v106
	v_log_f32_e32 v107, v107
	v_lshl_add_u64 v[112:113], v[122:123], 0, v[172:173]
	v_pk_mul_f32 v[238:239], v[108:109], s[0:1] op_sel_hi:[1,0]
	v_pk_mul_f32 v[240:241], v[110:111], s[0:1] op_sel_hi:[1,0]
	v_pk_mul_f32 v[242:243], v[104:105], s[0:1] op_sel_hi:[1,0]
	v_pk_mul_f32 v[244:245], v[106:107], s[0:1] op_sel_hi:[1,0]
	v_pk_fma_f32 v[238:239], v[108:109], s[0:1], v[238:239] op_sel_hi:[1,0,1] neg_lo:[0,0,1] neg_hi:[0,0,1]
	v_pk_fma_f32 v[240:241], v[110:111], s[0:1], v[240:241] op_sel_hi:[1,0,1] neg_lo:[0,0,1] neg_hi:[0,0,1]
	v_pk_fma_f32 v[242:243], v[104:105], s[0:1], v[242:243] op_sel_hi:[1,0,1] neg_lo:[0,0,1] neg_hi:[0,0,1]
	v_pk_fma_f32 v[244:245], v[106:107], s[0:1], v[244:245] op_sel_hi:[1,0,1] neg_lo:[0,0,1] neg_hi:[0,0,1]
	v_pk_fma_f32 v[238:239], v[108:109], s[6:7], v[238:239] op_sel_hi:[1,0,1]
	v_pk_fma_f32 v[240:241], v[110:111], s[6:7], v[240:241] op_sel_hi:[1,0,1]
	v_pk_fma_f32 v[242:243], v[104:105], s[6:7], v[242:243] op_sel_hi:[1,0,1]
	v_pk_fma_f32 v[244:245], v[106:107], s[6:7], v[244:245] op_sel_hi:[1,0,1]
	v_pk_fma_f32 v[238:239], v[108:109], s[0:1], v[238:239] op_sel_hi:[1,0,1]
	v_pk_fma_f32 v[240:241], v[110:111], s[0:1], v[240:241] op_sel_hi:[1,0,1]
	v_pk_fma_f32 v[242:243], v[104:105], s[0:1], v[242:243] op_sel_hi:[1,0,1]
	v_pk_fma_f32 v[244:245], v[106:107], s[0:1], v[244:245] op_sel_hi:[1,0,1]
	v_pk_add_f32 v[108:109], v[230:231], v[238:239] neg_lo:[0,1] neg_hi:[0,1]
	v_pk_add_f32 v[110:111], v[232:233], v[240:241] neg_lo:[0,1] neg_hi:[0,1]
	v_pk_add_f32 v[104:105], v[234:235], v[242:243] neg_lo:[0,1] neg_hi:[0,1]
	v_pk_add_f32 v[106:107], v[236:237], v[244:245] neg_lo:[0,1] neg_hi:[0,1]
	v_pk_mul_f32 v[108:109], v[108:109], s[2:3] op_sel_hi:[1,0]
	v_pk_mul_f32 v[110:111], v[110:111], s[2:3] op_sel_hi:[1,0]
	v_pk_mul_f32 v[104:105], v[104:105], s[2:3] op_sel_hi:[1,0]
	v_pk_mul_f32 v[106:107], v[106:107], s[2:3] op_sel_hi:[1,0]
	s_mov_b32 s0, 0x7f800000
	s_mov_b64 s[6:7], exec
	s_mov_b64 vcc, 0
	global_store_dwordx4 v[112:113], v[108:111], off
	global_store_dwordx4 v[112:113], v[104:107], off offset:16

.LBB0_751:
	s_and_b64 vcc, exec, s[0:1]
	s_cbranch_vccz .LBB0_753
	s_mov_b32 s0, 0x3f317217
	s_mov_b32 s2, 0x3d800000
	s_mov_b32 s6, 0x3377d1cf
	s_mov_b32 s98, 1.0
	v_mov_b32_e32 v173, v177
	v_pk_add_f32 v[100:101], v[100:101], v[226:227]
	v_pk_add_f32 v[102:103], v[102:103], v[228:229]
	v_pk_add_f32 v[96:97], v[96:97], v[222:223]
	v_pk_add_f32 v[98:99], v[98:99], v[224:225]
	v_min_f32_e32 v230, 0, v100
	v_min_f32_e32 v231, 0, v101
	v_min_f32_e32 v232, 0, v102
	v_min_f32_e32 v233, 0, v103
	v_min_f32_e32 v234, 0, v96
	v_min_f32_e32 v235, 0, v97
	v_min_f32_e32 v236, 0, v98
	v_min_f32_e32 v237, 0, v99
	v_mul_f32_e64 v100, |v100|, s70
	v_mul_f32_e64 v101, |v101|, s70
	v_mul_f32_e64 v102, |v102|, s70
	v_mul_f32_e64 v103, |v103|, s70
	v_mul_f32_e64 v96, |v96|, s70
	v_mul_f32_e64 v97, |v97|, s70
	v_mul_f32_e64 v98, |v98|, s70
	v_mul_f32_e64 v99, |v99|, s70
	v_exp_f32_e32 v100, v100
	v_exp_f32_e32 v101, v101
	v_exp_f32_e32 v102, v102
	v_exp_f32_e32 v103, v103
	v_exp_f32_e32 v96, v96
	v_exp_f32_e32 v97, v97
	v_exp_f32_e32 v98, v98
	v_exp_f32_e32 v99, v99
	v_pk_add_f32 v[100:101], v[100:101], s[98:99] op_sel_hi:[1,0]
	v_pk_add_f32 v[102:103], v[102:103], s[98:99] op_sel_hi:[1,0]
	v_pk_add_f32 v[96:97], v[96:97], s[98:99] op_sel_hi:[1,0]
	v_pk_add_f32 v[98:99], v[98:99], s[98:99] op_sel_hi:[1,0]
	v_log_f32_e32 v100, v100
	v_log_f32_e32 v101, v101
	v_log_f32_e32 v102, v102
	v_log_f32_e32 v103, v103
	v_log_f32_e32 v96, v96
	v_log_f32_e32 v97, v97
	v_log_f32_e32 v98, v98
	v_log_f32_e32 v99, v99
	v_lshl_add_u64 v[104:105], v[122:123], 0, v[172:173]
	v_pk_mul_f32 v[238:239], v[100:101], s[0:1] op_sel_hi:[1,0]
	v_pk_mul_f32 v[240:241], v[102:103], s[0:1] op_sel_hi:[1,0]
	v_pk_mul_f32 v[242:243], v[96:97], s[0:1] op_sel_hi:[1,0]
	v_pk_mul_f32 v[244:245], v[98:99], s[0:1] op_sel_hi:[1,0]
	v_pk_fma_f32 v[238:239], v[100:101], s[0:1], v[238:239] op_sel_hi:[1,0,1] neg_lo:[0,0,1] neg_hi:[0,0,1]
	v_pk_fma_f32 v[240:241], v[102:103], s[0:1], v[240:241] op_sel_hi:[1,0,1] neg_lo:[0,0,1] neg_hi:[0,0,1]
	v_pk_fma_f32 v[242:243], v[96:97], s[0:1], v[242:243] op_sel_hi:[1,0,1] neg_lo:[0,0,1] neg_hi:[0,0,1]
	v_pk_fma_f32 v[244:245], v[98:99], s[0:1], v[244:245] op_sel_hi:[1,0,1] neg_lo:[0,0,1] neg_hi:[0,0,1]
	v_pk_fma_f32 v[238:239], v[100:101], s[6:7], v[238:239] op_sel_hi:[1,0,1]
	v_pk_fma_f32 v[240:241], v[102:103], s[6:7], v[240:241] op_sel_hi:[1,0,1]
	v_pk_fma_f32 v[242:243], v[96:97], s[6:7], v[242:243] op_sel_hi:[1,0,1]
	v_pk_fma_f32 v[244:245], v[98:99], s[6:7], v[244:245] op_sel_hi:[1,0,1]
	v_pk_fma_f32 v[238:239], v[100:101], s[0:1], v[238:239] op_sel_hi:[1,0,1]
	v_pk_fma_f32 v[240:241], v[102:103], s[0:1], v[240:241] op_sel_hi:[1,0,1]
	v_pk_fma_f32 v[242:243], v[96:97], s[0:1], v[242:243] op_sel_hi:[1,0,1]
	v_pk_fma_f32 v[244:245], v[98:99], s[0:1], v[244:245] op_sel_hi:[1,0,1]
	v_pk_add_f32 v[100:101], v[230:231], v[238:239] neg_lo:[0,1] neg_hi:[0,1]
	v_pk_add_f32 v[102:103], v[232:233], v[240:241] neg_lo:[0,1] neg_hi:[0,1]
	v_pk_add_f32 v[96:97], v[234:235], v[242:243] neg_lo:[0,1] neg_hi:[0,1]
	v_pk_add_f32 v[98:99], v[236:237], v[244:245] neg_lo:[0,1] neg_hi:[0,1]
	v_pk_mul_f32 v[100:101], v[100:101], s[2:3] op_sel_hi:[1,0]
	v_pk_mul_f32 v[102:103], v[102:103], s[2:3] op_sel_hi:[1,0]
	v_pk_mul_f32 v[96:97], v[96:97], s[2:3] op_sel_hi:[1,0]
	v_pk_mul_f32 v[98:99], v[98:99], s[2:3] op_sel_hi:[1,0]
	s_mov_b32 s0, 0x7f800000
	s_mov_b64 s[6:7], exec
	s_mov_b64 vcc, 0
	global_store_dwordx4 v[104:105], v[100:103], off offset:512
	global_store_dwordx4 v[104:105], v[96:99], off offset:528

.LBB0_776:
	s_nop 1
	v_lshlrev_b64 v[96:97], 10, v[104:105]
	s_and_b64 vcc, exec, s[0:1]
	v_lshl_add_u64 v[104:105], s[8:9], 0, v[96:97]
	s_cbranch_vccz .LBB0_778
	s_mov_b32 s0, 0x3f317217
	s_mov_b32 s2, 0x3d800000
	s_mov_b32 s6, 0x3377d1cf
	s_mov_b32 s98, 1.0
	v_mov_b32_e32 v173, v177
	v_pk_add_f32 v[92:93], v[92:93], v[218:219]
	v_pk_add_f32 v[94:95], v[94:95], v[220:221]
	v_pk_add_f32 v[88:89], v[88:89], v[214:215]
	v_pk_add_f32 v[90:91], v[90:91], v[216:217]
	v_min_f32_e32 v230, 0, v92
	v_min_f32_e32 v231, 0, v93
	v_min_f32_e32 v232, 0, v94
	v_min_f32_e32 v233, 0, v95
	v_min_f32_e32 v234, 0, v88
	v_min_f32_e32 v235, 0, v89
	v_min_f32_e32 v236, 0, v90
	v_min_f32_e32 v237, 0, v91
	v_mul_f32_e64 v92, |v92|, s70
	v_mul_f32_e64 v93, |v93|, s70
	v_mul_f32_e64 v94, |v94|, s70
	v_mul_f32_e64 v95, |v95|, s70
	v_mul_f32_e64 v88, |v88|, s70
	v_mul_f32_e64 v89, |v89|, s70
	v_mul_f32_e64 v90, |v90|, s70
	v_mul_f32_e64 v91, |v91|, s70
	v_exp_f32_e32 v92, v92
	v_exp_f32_e32 v93, v93
	v_exp_f32_e32 v94, v94
	v_exp_f32_e32 v95, v95
	v_exp_f32_e32 v88, v88
	v_exp_f32_e32 v89, v89
	v_exp_f32_e32 v90, v90
	v_exp_f32_e32 v91, v91
	v_pk_add_f32 v[92:93], v[92:93], s[98:99] op_sel_hi:[1,0]
	v_pk_add_f32 v[94:95], v[94:95], s[98:99] op_sel_hi:[1,0]
	v_pk_add_f32 v[88:89], v[88:89], s[98:99] op_sel_hi:[1,0]
	v_pk_add_f32 v[90:91], v[90:91], s[98:99] op_sel_hi:[1,0]
	v_log_f32_e32 v92, v92
	v_log_f32_e32 v93, v93
	v_log_f32_e32 v94, v94
	v_log_f32_e32 v95, v95
	v_log_f32_e32 v88, v88
	v_log_f32_e32 v89, v89
	v_log_f32_e32 v90, v90
	v_log_f32_e32 v91, v91
	v_lshl_add_u64 v[96:97], v[104:105], 0, v[172:173]
	v_pk_mul_f32 v[238:239], v[92:93], s[0:1] op_sel_hi:[1,0]
	v_pk_mul_f32 v[240:241], v[94:95], s[0:1] op_sel_hi:[1,0]
	v_pk_mul_f32 v[242:243], v[88:89], s[0:1] op_sel_hi:[1,0]
	v_pk_mul_f32 v[244:245], v[90:91], s[0:1] op_sel_hi:[1,0]
	v_pk_fma_f32 v[238:239], v[92:93], s[0:1], v[238:239] op_sel_hi:[1,0,1] neg_lo:[0,0,1] neg_hi:[0,0,1]
	v_pk_fma_f32 v[240:241], v[94:95], s[0:1], v[240:241] op_sel_hi:[1,0,1] neg_lo:[0,0,1] neg_hi:[0,0,1]
	v_pk_fma_f32 v[242:243], v[88:89], s[0:1], v[242:243] op_sel_hi:[1,0,1] neg_lo:[0,0,1] neg_hi:[0,0,1]
	v_pk_fma_f32 v[244:245], v[90:91], s[0:1], v[244:245] op_sel_hi:[1,0,1] neg_lo:[0,0,1] neg_hi:[0,0,1]
	v_pk_fma_f32 v[238:239], v[92:93], s[6:7], v[238:239] op_sel_hi:[1,0,1]
	v_pk_fma_f32 v[240:241], v[94:95], s[6:7], v[240:241] op_sel_hi:[1,0,1]
	v_pk_fma_f32 v[242:243], v[88:89], s[6:7], v[242:243] op_sel_hi:[1,0,1]
	v_pk_fma_f32 v[244:245], v[90:91], s[6:7], v[244:245] op_sel_hi:[1,0,1]
	v_pk_fma_f32 v[238:239], v[92:93], s[0:1], v[238:239] op_sel_hi:[1,0,1]
	v_pk_fma_f32 v[240:241], v[94:95], s[0:1], v[240:241] op_sel_hi:[1,0,1]
	v_pk_fma_f32 v[242:243], v[88:89], s[0:1], v[242:243] op_sel_hi:[1,0,1]
	v_pk_fma_f32 v[244:245], v[90:91], s[0:1], v[244:245] op_sel_hi:[1,0,1]
	v_pk_add_f32 v[92:93], v[230:231], v[238:239] neg_lo:[0,1] neg_hi:[0,1]
	v_pk_add_f32 v[94:95], v[232:233], v[240:241] neg_lo:[0,1] neg_hi:[0,1]
	v_pk_add_f32 v[88:89], v[234:235], v[242:243] neg_lo:[0,1] neg_hi:[0,1]
	v_pk_add_f32 v[90:91], v[236:237], v[244:245] neg_lo:[0,1] neg_hi:[0,1]
	v_pk_mul_f32 v[92:93], v[92:93], s[2:3] op_sel_hi:[1,0]
	v_pk_mul_f32 v[94:95], v[94:95], s[2:3] op_sel_hi:[1,0]
	v_pk_mul_f32 v[88:89], v[88:89], s[2:3] op_sel_hi:[1,0]
	v_pk_mul_f32 v[90:91], v[90:91], s[2:3] op_sel_hi:[1,0]
	s_mov_b32 s0, 0x7f800000
	s_mov_b64 s[6:7], exec
	s_mov_b64 vcc, 0
	global_store_dwordx4 v[96:97], v[92:95], off
	global_store_dwordx4 v[96:97], v[88:91], off offset:16

.LBB0_791:
	s_and_b64 vcc, exec, s[0:1]
	s_cbranch_vccz .LBB0_793
	s_mov_b32 s0, 0x3f317217
	s_mov_b32 s2, 0x3d800000
	s_mov_b32 s6, 0x3377d1cf
	s_mov_b32 s98, 1.0
	v_mov_b32_e32 v173, v177
	v_pk_add_f32 v[84:85], v[84:85], v[226:227]
	v_pk_add_f32 v[86:87], v[86:87], v[228:229]
	v_pk_add_f32 v[80:81], v[80:81], v[222:223]
	v_pk_add_f32 v[82:83], v[82:83], v[224:225]
	v_min_f32_e32 v230, 0, v84
	v_min_f32_e32 v231, 0, v85
	v_min_f32_e32 v232, 0, v86
	v_min_f32_e32 v233, 0, v87
	v_min_f32_e32 v234, 0, v80
	v_min_f32_e32 v235, 0, v81
	v_min_f32_e32 v236, 0, v82
	v_min_f32_e32 v237, 0, v83
	v_mul_f32_e64 v84, |v84|, s70
	v_mul_f32_e64 v85, |v85|, s70
	v_mul_f32_e64 v86, |v86|, s70
	v_mul_f32_e64 v87, |v87|, s70
	v_mul_f32_e64 v80, |v80|, s70
	v_mul_f32_e64 v81, |v81|, s70
	v_mul_f32_e64 v82, |v82|, s70
	v_mul_f32_e64 v83, |v83|, s70
	v_exp_f32_e32 v84, v84
	v_exp_f32_e32 v85, v85
	v_exp_f32_e32 v86, v86
	v_exp_f32_e32 v87, v87
	v_exp_f32_e32 v80, v80
	v_exp_f32_e32 v81, v81
	v_exp_f32_e32 v82, v82
	v_exp_f32_e32 v83, v83
	v_pk_add_f32 v[84:85], v[84:85], s[98:99] op_sel_hi:[1,0]
	v_pk_add_f32 v[86:87], v[86:87], s[98:99] op_sel_hi:[1,0]
	v_pk_add_f32 v[80:81], v[80:81], s[98:99] op_sel_hi:[1,0]
	v_pk_add_f32 v[82:83], v[82:83], s[98:99] op_sel_hi:[1,0]
	v_log_f32_e32 v84, v84
	v_log_f32_e32 v85, v85
	v_log_f32_e32 v86, v86
	v_log_f32_e32 v87, v87
	v_log_f32_e32 v80, v80
	v_log_f32_e32 v81, v81
	v_log_f32_e32 v82, v82
	v_log_f32_e32 v83, v83
	v_lshl_add_u64 v[88:89], v[104:105], 0, v[172:173]
	v_pk_mul_f32 v[238:239], v[84:85], s[0:1] op_sel_hi:[1,0]
	v_pk_mul_f32 v[240:241], v[86:87], s[0:1] op_sel_hi:[1,0]
	v_pk_mul_f32 v[242:243], v[80:81], s[0:1] op_sel_hi:[1,0]
	v_pk_mul_f32 v[244:245], v[82:83], s[0:1] op_sel_hi:[1,0]
	v_pk_fma_f32 v[238:239], v[84:85], s[0:1], v[238:239] op_sel_hi:[1,0,1] neg_lo:[0,0,1] neg_hi:[0,0,1]
	v_pk_fma_f32 v[240:241], v[86:87], s[0:1], v[240:241] op_sel_hi:[1,0,1] neg_lo:[0,0,1] neg_hi:[0,0,1]
	v_pk_fma_f32 v[242:243], v[80:81], s[0:1], v[242:243] op_sel_hi:[1,0,1] neg_lo:[0,0,1] neg_hi:[0,0,1]
	v_pk_fma_f32 v[244:245], v[82:83], s[0:1], v[244:245] op_sel_hi:[1,0,1] neg_lo:[0,0,1] neg_hi:[0,0,1]
	v_pk_fma_f32 v[238:239], v[84:85], s[6:7], v[238:239] op_sel_hi:[1,0,1]
	v_pk_fma_f32 v[240:241], v[86:87], s[6:7], v[240:241] op_sel_hi:[1,0,1]
	v_pk_fma_f32 v[242:243], v[80:81], s[6:7], v[242:243] op_sel_hi:[1,0,1]
	v_pk_fma_f32 v[244:245], v[82:83], s[6:7], v[244:245] op_sel_hi:[1,0,1]
	v_pk_fma_f32 v[238:239], v[84:85], s[0:1], v[238:239] op_sel_hi:[1,0,1]
	v_pk_fma_f32 v[240:241], v[86:87], s[0:1], v[240:241] op_sel_hi:[1,0,1]
	v_pk_fma_f32 v[242:243], v[80:81], s[0:1], v[242:243] op_sel_hi:[1,0,1]
	v_pk_fma_f32 v[244:245], v[82:83], s[0:1], v[244:245] op_sel_hi:[1,0,1]
	v_pk_add_f32 v[84:85], v[230:231], v[238:239] neg_lo:[0,1] neg_hi:[0,1]
	v_pk_add_f32 v[86:87], v[232:233], v[240:241] neg_lo:[0,1] neg_hi:[0,1]
	v_pk_add_f32 v[80:81], v[234:235], v[242:243] neg_lo:[0,1] neg_hi:[0,1]
	v_pk_add_f32 v[82:83], v[236:237], v[244:245] neg_lo:[0,1] neg_hi:[0,1]
	v_pk_mul_f32 v[84:85], v[84:85], s[2:3] op_sel_hi:[1,0]
	v_pk_mul_f32 v[86:87], v[86:87], s[2:3] op_sel_hi:[1,0]
	v_pk_mul_f32 v[80:81], v[80:81], s[2:3] op_sel_hi:[1,0]
	v_pk_mul_f32 v[82:83], v[82:83], s[2:3] op_sel_hi:[1,0]
	s_mov_b32 s0, 0x7f800000
	s_mov_b64 s[6:7], exec
	s_mov_b64 vcc, 0
	global_store_dwordx4 v[88:89], v[84:87], off offset:512
	global_store_dwordx4 v[88:89], v[80:83], off offset:528

.LBB0_816:
	s_nop 1
	v_lshlrev_b64 v[72:73], 10, v[82:83]
	s_and_b64 vcc, exec, s[0:1]
	v_lshl_add_u64 v[82:83], s[8:9], 0, v[72:73]
	s_cbranch_vccz .LBB0_818
	s_mov_b32 s0, 0x3f317217
	s_mov_b32 s2, 0x3d800000
	s_mov_b32 s6, 0x3377d1cf
	s_mov_b32 s98, 1.0
	v_mov_b32_e32 v173, v177
	v_pk_add_f32 v[68:69], v[68:69], v[218:219]
	v_pk_add_f32 v[70:71], v[70:71], v[220:221]
	v_pk_add_f32 v[64:65], v[64:65], v[214:215]
	v_pk_add_f32 v[66:67], v[66:67], v[216:217]
	v_min_f32_e32 v230, 0, v68
	v_min_f32_e32 v231, 0, v69
	v_min_f32_e32 v232, 0, v70
	v_min_f32_e32 v233, 0, v71
	v_min_f32_e32 v234, 0, v64
	v_min_f32_e32 v235, 0, v65
	v_min_f32_e32 v236, 0, v66
	v_min_f32_e32 v237, 0, v67
	v_mul_f32_e64 v68, |v68|, s70
	v_mul_f32_e64 v69, |v69|, s70
	v_mul_f32_e64 v70, |v70|, s70
	v_mul_f32_e64 v71, |v71|, s70
	v_mul_f32_e64 v64, |v64|, s70
	v_mul_f32_e64 v65, |v65|, s70
	v_mul_f32_e64 v66, |v66|, s70
	v_mul_f32_e64 v67, |v67|, s70
	v_exp_f32_e32 v68, v68
	v_exp_f32_e32 v69, v69
	v_exp_f32_e32 v70, v70
	v_exp_f32_e32 v71, v71
	v_exp_f32_e32 v64, v64
	v_exp_f32_e32 v65, v65
	v_exp_f32_e32 v66, v66
	v_exp_f32_e32 v67, v67
	v_pk_add_f32 v[68:69], v[68:69], s[98:99] op_sel_hi:[1,0]
	v_pk_add_f32 v[70:71], v[70:71], s[98:99] op_sel_hi:[1,0]
	v_pk_add_f32 v[64:65], v[64:65], s[98:99] op_sel_hi:[1,0]
	v_pk_add_f32 v[66:67], v[66:67], s[98:99] op_sel_hi:[1,0]
	v_log_f32_e32 v68, v68
	v_log_f32_e32 v69, v69
	v_log_f32_e32 v70, v70
	v_log_f32_e32 v71, v71
	v_log_f32_e32 v64, v64
	v_log_f32_e32 v65, v65
	v_log_f32_e32 v66, v66
	v_log_f32_e32 v67, v67
	v_lshl_add_u64 v[72:73], v[82:83], 0, v[172:173]
	v_pk_mul_f32 v[238:239], v[68:69], s[0:1] op_sel_hi:[1,0]
	v_pk_mul_f32 v[240:241], v[70:71], s[0:1] op_sel_hi:[1,0]
	v_pk_mul_f32 v[242:243], v[64:65], s[0:1] op_sel_hi:[1,0]
	v_pk_mul_f32 v[244:245], v[66:67], s[0:1] op_sel_hi:[1,0]
	v_pk_fma_f32 v[238:239], v[68:69], s[0:1], v[238:239] op_sel_hi:[1,0,1] neg_lo:[0,0,1] neg_hi:[0,0,1]
	v_pk_fma_f32 v[240:241], v[70:71], s[0:1], v[240:241] op_sel_hi:[1,0,1] neg_lo:[0,0,1] neg_hi:[0,0,1]
	v_pk_fma_f32 v[242:243], v[64:65], s[0:1], v[242:243] op_sel_hi:[1,0,1] neg_lo:[0,0,1] neg_hi:[0,0,1]
	v_pk_fma_f32 v[244:245], v[66:67], s[0:1], v[244:245] op_sel_hi:[1,0,1] neg_lo:[0,0,1] neg_hi:[0,0,1]
	v_pk_fma_f32 v[238:239], v[68:69], s[6:7], v[238:239] op_sel_hi:[1,0,1]
	v_pk_fma_f32 v[240:241], v[70:71], s[6:7], v[240:241] op_sel_hi:[1,0,1]
	v_pk_fma_f32 v[242:243], v[64:65], s[6:7], v[242:243] op_sel_hi:[1,0,1]
	v_pk_fma_f32 v[244:245], v[66:67], s[6:7], v[244:245] op_sel_hi:[1,0,1]
	v_pk_fma_f32 v[238:239], v[68:69], s[0:1], v[238:239] op_sel_hi:[1,0,1]
	v_pk_fma_f32 v[240:241], v[70:71], s[0:1], v[240:241] op_sel_hi:[1,0,1]
	v_pk_fma_f32 v[242:243], v[64:65], s[0:1], v[242:243] op_sel_hi:[1,0,1]
	v_pk_fma_f32 v[244:245], v[66:67], s[0:1], v[244:245] op_sel_hi:[1,0,1]
	v_pk_add_f32 v[68:69], v[230:231], v[238:239] neg_lo:[0,1] neg_hi:[0,1]
	v_pk_add_f32 v[70:71], v[232:233], v[240:241] neg_lo:[0,1] neg_hi:[0,1]
	v_pk_add_f32 v[64:65], v[234:235], v[242:243] neg_lo:[0,1] neg_hi:[0,1]
	v_pk_add_f32 v[66:67], v[236:237], v[244:245] neg_lo:[0,1] neg_hi:[0,1]
	v_pk_mul_f32 v[68:69], v[68:69], s[2:3] op_sel_hi:[1,0]
	v_pk_mul_f32 v[70:71], v[70:71], s[2:3] op_sel_hi:[1,0]
	v_pk_mul_f32 v[64:65], v[64:65], s[2:3] op_sel_hi:[1,0]
	v_pk_mul_f32 v[66:67], v[66:67], s[2:3] op_sel_hi:[1,0]
	s_mov_b32 s0, 0x7f800000
	s_mov_b64 s[6:7], exec
	s_mov_b64 vcc, 0
	global_store_dwordx4 v[72:73], v[68:71], off
	global_store_dwordx4 v[72:73], v[64:67], off offset:16

.LBB0_831:
	s_and_b64 vcc, exec, s[0:1]
	s_cbranch_vccz .LBB0_833
	s_mov_b32 s0, 0x3f317217
	s_mov_b32 s2, 0x3d800000
	s_mov_b32 s6, 0x3377d1cf
	s_mov_b32 s98, 1.0
	v_mov_b32_e32 v173, v177
	v_pk_add_f32 v[60:61], v[60:61], v[226:227]
	v_pk_add_f32 v[62:63], v[62:63], v[228:229]
	v_pk_add_f32 v[56:57], v[56:57], v[222:223]
	v_pk_add_f32 v[58:59], v[58:59], v[224:225]
	v_min_f32_e32 v230, 0, v60
	v_min_f32_e32 v231, 0, v61
	v_min_f32_e32 v232, 0, v62
	v_min_f32_e32 v233, 0, v63
	v_min_f32_e32 v234, 0, v56
	v_min_f32_e32 v235, 0, v57
	v_min_f32_e32 v236, 0, v58
	v_min_f32_e32 v237, 0, v59
	v_mul_f32_e64 v60, |v60|, s70
	v_mul_f32_e64 v61, |v61|, s70
	v_mul_f32_e64 v62, |v62|, s70
	v_mul_f32_e64 v63, |v63|, s70
	v_mul_f32_e64 v56, |v56|, s70
	v_mul_f32_e64 v57, |v57|, s70
	v_mul_f32_e64 v58, |v58|, s70
	v_mul_f32_e64 v59, |v59|, s70
	v_exp_f32_e32 v60, v60
	v_exp_f32_e32 v61, v61
	v_exp_f32_e32 v62, v62
	v_exp_f32_e32 v63, v63
	v_exp_f32_e32 v56, v56
	v_exp_f32_e32 v57, v57
	v_exp_f32_e32 v58, v58
	v_exp_f32_e32 v59, v59
	v_pk_add_f32 v[60:61], v[60:61], s[98:99] op_sel_hi:[1,0]
	v_pk_add_f32 v[62:63], v[62:63], s[98:99] op_sel_hi:[1,0]
	v_pk_add_f32 v[56:57], v[56:57], s[98:99] op_sel_hi:[1,0]
	v_pk_add_f32 v[58:59], v[58:59], s[98:99] op_sel_hi:[1,0]
	v_log_f32_e32 v60, v60
	v_log_f32_e32 v61, v61
	v_log_f32_e32 v62, v62
	v_log_f32_e32 v63, v63
	v_log_f32_e32 v56, v56
	v_log_f32_e32 v57, v57
	v_log_f32_e32 v58, v58
	v_log_f32_e32 v59, v59
	v_lshl_add_u64 v[64:65], v[82:83], 0, v[172:173]
	v_pk_mul_f32 v[238:239], v[60:61], s[0:1] op_sel_hi:[1,0]
	v_pk_mul_f32 v[240:241], v[62:63], s[0:1] op_sel_hi:[1,0]
	v_pk_mul_f32 v[242:243], v[56:57], s[0:1] op_sel_hi:[1,0]
	v_pk_mul_f32 v[244:245], v[58:59], s[0:1] op_sel_hi:[1,0]
	v_pk_fma_f32 v[238:239], v[60:61], s[0:1], v[238:239] op_sel_hi:[1,0,1] neg_lo:[0,0,1] neg_hi:[0,0,1]
	v_pk_fma_f32 v[240:241], v[62:63], s[0:1], v[240:241] op_sel_hi:[1,0,1] neg_lo:[0,0,1] neg_hi:[0,0,1]
	v_pk_fma_f32 v[242:243], v[56:57], s[0:1], v[242:243] op_sel_hi:[1,0,1] neg_lo:[0,0,1] neg_hi:[0,0,1]
	v_pk_fma_f32 v[244:245], v[58:59], s[0:1], v[244:245] op_sel_hi:[1,0,1] neg_lo:[0,0,1] neg_hi:[0,0,1]
	v_pk_fma_f32 v[238:239], v[60:61], s[6:7], v[238:239] op_sel_hi:[1,0,1]
	v_pk_fma_f32 v[240:241], v[62:63], s[6:7], v[240:241] op_sel_hi:[1,0,1]
	v_pk_fma_f32 v[242:243], v[56:57], s[6:7], v[242:243] op_sel_hi:[1,0,1]
	v_pk_fma_f32 v[244:245], v[58:59], s[6:7], v[244:245] op_sel_hi:[1,0,1]
	v_pk_fma_f32 v[238:239], v[60:61], s[0:1], v[238:239] op_sel_hi:[1,0,1]
	v_pk_fma_f32 v[240:241], v[62:63], s[0:1], v[240:241] op_sel_hi:[1,0,1]
	v_pk_fma_f32 v[242:243], v[56:57], s[0:1], v[242:243] op_sel_hi:[1,0,1]
	v_pk_fma_f32 v[244:245], v[58:59], s[0:1], v[244:245] op_sel_hi:[1,0,1]
	v_pk_add_f32 v[60:61], v[230:231], v[238:239] neg_lo:[0,1] neg_hi:[0,1]
	v_pk_add_f32 v[62:63], v[232:233], v[240:241] neg_lo:[0,1] neg_hi:[0,1]
	v_pk_add_f32 v[56:57], v[234:235], v[242:243] neg_lo:[0,1] neg_hi:[0,1]
	v_pk_add_f32 v[58:59], v[236:237], v[244:245] neg_lo:[0,1] neg_hi:[0,1]
	v_pk_mul_f32 v[60:61], v[60:61], s[2:3] op_sel_hi:[1,0]
	v_pk_mul_f32 v[62:63], v[62:63], s[2:3] op_sel_hi:[1,0]
	v_pk_mul_f32 v[56:57], v[56:57], s[2:3] op_sel_hi:[1,0]
	v_pk_mul_f32 v[58:59], v[58:59], s[2:3] op_sel_hi:[1,0]
	s_mov_b32 s0, 0x7f800000
	s_mov_b64 s[6:7], exec
	s_mov_b64 vcc, 0
	global_store_dwordx4 v[64:65], v[60:63], off offset:512
	global_store_dwordx4 v[64:65], v[56:59], off offset:528

.LBB0_856:
	s_nop 1
	v_lshlrev_b64 v[56:57], 10, v[64:65]
	s_and_b64 vcc, exec, s[0:1]
	v_lshl_add_u64 v[64:65], s[8:9], 0, v[56:57]
	s_cbranch_vccz .LBB0_858
	s_mov_b32 s0, 0x3f317217
	s_mov_b32 s2, 0x3d800000
	s_mov_b32 s6, 0x3377d1cf
	s_mov_b32 s98, 1.0
	v_mov_b32_e32 v173, v177
	v_pk_add_f32 v[52:53], v[52:53], v[218:219]
	v_pk_add_f32 v[54:55], v[54:55], v[220:221]
	v_pk_add_f32 v[48:49], v[48:49], v[214:215]
	v_pk_add_f32 v[50:51], v[50:51], v[216:217]
	v_min_f32_e32 v230, 0, v52
	v_min_f32_e32 v231, 0, v53
	v_min_f32_e32 v232, 0, v54
	v_min_f32_e32 v233, 0, v55
	v_min_f32_e32 v234, 0, v48
	v_min_f32_e32 v235, 0, v49
	v_min_f32_e32 v236, 0, v50
	v_min_f32_e32 v237, 0, v51
	v_mul_f32_e64 v52, |v52|, s70
	v_mul_f32_e64 v53, |v53|, s70
	v_mul_f32_e64 v54, |v54|, s70
	v_mul_f32_e64 v55, |v55|, s70
	v_mul_f32_e64 v48, |v48|, s70
	v_mul_f32_e64 v49, |v49|, s70
	v_mul_f32_e64 v50, |v50|, s70
	v_mul_f32_e64 v51, |v51|, s70
	v_exp_f32_e32 v52, v52
	v_exp_f32_e32 v53, v53
	v_exp_f32_e32 v54, v54
	v_exp_f32_e32 v55, v55
	v_exp_f32_e32 v48, v48
	v_exp_f32_e32 v49, v49
	v_exp_f32_e32 v50, v50
	v_exp_f32_e32 v51, v51
	v_pk_add_f32 v[52:53], v[52:53], s[98:99] op_sel_hi:[1,0]
	v_pk_add_f32 v[54:55], v[54:55], s[98:99] op_sel_hi:[1,0]
	v_pk_add_f32 v[48:49], v[48:49], s[98:99] op_sel_hi:[1,0]
	v_pk_add_f32 v[50:51], v[50:51], s[98:99] op_sel_hi:[1,0]
	v_log_f32_e32 v52, v52
	v_log_f32_e32 v53, v53
	v_log_f32_e32 v54, v54
	v_log_f32_e32 v55, v55
	v_log_f32_e32 v48, v48
	v_log_f32_e32 v49, v49
	v_log_f32_e32 v50, v50
	v_log_f32_e32 v51, v51
	v_lshl_add_u64 v[56:57], v[64:65], 0, v[172:173]
	v_pk_mul_f32 v[238:239], v[52:53], s[0:1] op_sel_hi:[1,0]
	v_pk_mul_f32 v[240:241], v[54:55], s[0:1] op_sel_hi:[1,0]
	v_pk_mul_f32 v[242:243], v[48:49], s[0:1] op_sel_hi:[1,0]
	v_pk_mul_f32 v[244:245], v[50:51], s[0:1] op_sel_hi:[1,0]
	v_pk_fma_f32 v[238:239], v[52:53], s[0:1], v[238:239] op_sel_hi:[1,0,1] neg_lo:[0,0,1] neg_hi:[0,0,1]
	v_pk_fma_f32 v[240:241], v[54:55], s[0:1], v[240:241] op_sel_hi:[1,0,1] neg_lo:[0,0,1] neg_hi:[0,0,1]
	v_pk_fma_f32 v[242:243], v[48:49], s[0:1], v[242:243] op_sel_hi:[1,0,1] neg_lo:[0,0,1] neg_hi:[0,0,1]
	v_pk_fma_f32 v[244:245], v[50:51], s[0:1], v[244:245] op_sel_hi:[1,0,1] neg_lo:[0,0,1] neg_hi:[0,0,1]
	v_pk_fma_f32 v[238:239], v[52:53], s[6:7], v[238:239] op_sel_hi:[1,0,1]
	v_pk_fma_f32 v[240:241], v[54:55], s[6:7], v[240:241] op_sel_hi:[1,0,1]
	v_pk_fma_f32 v[242:243], v[48:49], s[6:7], v[242:243] op_sel_hi:[1,0,1]
	v_pk_fma_f32 v[244:245], v[50:51], s[6:7], v[244:245] op_sel_hi:[1,0,1]
	v_pk_fma_f32 v[238:239], v[52:53], s[0:1], v[238:239] op_sel_hi:[1,0,1]
	v_pk_fma_f32 v[240:241], v[54:55], s[0:1], v[240:241] op_sel_hi:[1,0,1]
	v_pk_fma_f32 v[242:243], v[48:49], s[0:1], v[242:243] op_sel_hi:[1,0,1]
	v_pk_fma_f32 v[244:245], v[50:51], s[0:1], v[244:245] op_sel_hi:[1,0,1]
	v_pk_add_f32 v[52:53], v[230:231], v[238:239] neg_lo:[0,1] neg_hi:[0,1]
	v_pk_add_f32 v[54:55], v[232:233], v[240:241] neg_lo:[0,1] neg_hi:[0,1]
	v_pk_add_f32 v[48:49], v[234:235], v[242:243] neg_lo:[0,1] neg_hi:[0,1]
	v_pk_add_f32 v[50:51], v[236:237], v[244:245] neg_lo:[0,1] neg_hi:[0,1]
	v_pk_mul_f32 v[52:53], v[52:53], s[2:3] op_sel_hi:[1,0]
	v_pk_mul_f32 v[54:55], v[54:55], s[2:3] op_sel_hi:[1,0]
	v_pk_mul_f32 v[48:49], v[48:49], s[2:3] op_sel_hi:[1,0]
	v_pk_mul_f32 v[50:51], v[50:51], s[2:3] op_sel_hi:[1,0]
	s_mov_b32 s0, 0x7f800000
	s_mov_b64 s[6:7], exec
	s_mov_b64 vcc, 0
	global_store_dwordx4 v[56:57], v[52:55], off
	global_store_dwordx4 v[56:57], v[48:51], off offset:16

.LBB0_871:
	s_and_b64 vcc, exec, s[0:1]
	s_cbranch_vccz .LBB0_873
	s_mov_b32 s0, 0x3f317217
	s_mov_b32 s2, 0x3d800000
	s_mov_b32 s6, 0x3377d1cf
	s_mov_b32 s98, 1.0
	v_mov_b32_e32 v173, v177
	v_pk_add_f32 v[44:45], v[44:45], v[226:227]
	v_pk_add_f32 v[46:47], v[46:47], v[228:229]
	v_pk_add_f32 v[40:41], v[40:41], v[222:223]
	v_pk_add_f32 v[42:43], v[42:43], v[224:225]
	v_min_f32_e32 v230, 0, v44
	v_min_f32_e32 v231, 0, v45
	v_min_f32_e32 v232, 0, v46
	v_min_f32_e32 v233, 0, v47
	v_min_f32_e32 v234, 0, v40
	v_min_f32_e32 v235, 0, v41
	v_min_f32_e32 v236, 0, v42
	v_min_f32_e32 v237, 0, v43
	v_mul_f32_e64 v44, |v44|, s70
	v_mul_f32_e64 v45, |v45|, s70
	v_mul_f32_e64 v46, |v46|, s70
	v_mul_f32_e64 v47, |v47|, s70
	v_mul_f32_e64 v40, |v40|, s70
	v_mul_f32_e64 v41, |v41|, s70
	v_mul_f32_e64 v42, |v42|, s70
	v_mul_f32_e64 v43, |v43|, s70
	v_exp_f32_e32 v44, v44
	v_exp_f32_e32 v45, v45
	v_exp_f32_e32 v46, v46
	v_exp_f32_e32 v47, v47
	v_exp_f32_e32 v40, v40
	v_exp_f32_e32 v41, v41
	v_exp_f32_e32 v42, v42
	v_exp_f32_e32 v43, v43
	v_pk_add_f32 v[44:45], v[44:45], s[98:99] op_sel_hi:[1,0]
	v_pk_add_f32 v[46:47], v[46:47], s[98:99] op_sel_hi:[1,0]
	v_pk_add_f32 v[40:41], v[40:41], s[98:99] op_sel_hi:[1,0]
	v_pk_add_f32 v[42:43], v[42:43], s[98:99] op_sel_hi:[1,0]
	v_log_f32_e32 v44, v44
	v_log_f32_e32 v45, v45
	v_log_f32_e32 v46, v46
	v_log_f32_e32 v47, v47
	v_log_f32_e32 v40, v40
	v_log_f32_e32 v41, v41
	v_log_f32_e32 v42, v42
	v_log_f32_e32 v43, v43
	v_lshl_add_u64 v[48:49], v[64:65], 0, v[172:173]
	v_pk_mul_f32 v[238:239], v[44:45], s[0:1] op_sel_hi:[1,0]
	v_pk_mul_f32 v[240:241], v[46:47], s[0:1] op_sel_hi:[1,0]
	v_pk_mul_f32 v[242:243], v[40:41], s[0:1] op_sel_hi:[1,0]
	v_pk_mul_f32 v[244:245], v[42:43], s[0:1] op_sel_hi:[1,0]
	v_pk_fma_f32 v[238:239], v[44:45], s[0:1], v[238:239] op_sel_hi:[1,0,1] neg_lo:[0,0,1] neg_hi:[0,0,1]
	v_pk_fma_f32 v[240:241], v[46:47], s[0:1], v[240:241] op_sel_hi:[1,0,1] neg_lo:[0,0,1] neg_hi:[0,0,1]
	v_pk_fma_f32 v[242:243], v[40:41], s[0:1], v[242:243] op_sel_hi:[1,0,1] neg_lo:[0,0,1] neg_hi:[0,0,1]
	v_pk_fma_f32 v[244:245], v[42:43], s[0:1], v[244:245] op_sel_hi:[1,0,1] neg_lo:[0,0,1] neg_hi:[0,0,1]
	v_pk_fma_f32 v[238:239], v[44:45], s[6:7], v[238:239] op_sel_hi:[1,0,1]
	v_pk_fma_f32 v[240:241], v[46:47], s[6:7], v[240:241] op_sel_hi:[1,0,1]
	v_pk_fma_f32 v[242:243], v[40:41], s[6:7], v[242:243] op_sel_hi:[1,0,1]
	v_pk_fma_f32 v[244:245], v[42:43], s[6:7], v[244:245] op_sel_hi:[1,0,1]
	v_pk_fma_f32 v[238:239], v[44:45], s[0:1], v[238:239] op_sel_hi:[1,0,1]
	v_pk_fma_f32 v[240:241], v[46:47], s[0:1], v[240:241] op_sel_hi:[1,0,1]
	v_pk_fma_f32 v[242:243], v[40:41], s[0:1], v[242:243] op_sel_hi:[1,0,1]
	v_pk_fma_f32 v[244:245], v[42:43], s[0:1], v[244:245] op_sel_hi:[1,0,1]
	v_pk_add_f32 v[44:45], v[230:231], v[238:239] neg_lo:[0,1] neg_hi:[0,1]
	v_pk_add_f32 v[46:47], v[232:233], v[240:241] neg_lo:[0,1] neg_hi:[0,1]
	v_pk_add_f32 v[40:41], v[234:235], v[242:243] neg_lo:[0,1] neg_hi:[0,1]
	v_pk_add_f32 v[42:43], v[236:237], v[244:245] neg_lo:[0,1] neg_hi:[0,1]
	v_pk_mul_f32 v[44:45], v[44:45], s[2:3] op_sel_hi:[1,0]
	v_pk_mul_f32 v[46:47], v[46:47], s[2:3] op_sel_hi:[1,0]
	v_pk_mul_f32 v[40:41], v[40:41], s[2:3] op_sel_hi:[1,0]
	v_pk_mul_f32 v[42:43], v[42:43], s[2:3] op_sel_hi:[1,0]
	s_mov_b32 s0, 0x7f800000
	s_mov_b64 s[6:7], exec
	s_mov_b64 vcc, 0
	global_store_dwordx4 v[48:49], v[44:47], off offset:512
	global_store_dwordx4 v[48:49], v[40:43], off offset:528

.LBB0_896:
	s_nop 1
	v_lshlrev_b64 v[32:33], 10, v[42:43]
	s_and_b64 vcc, exec, s[0:1]
	v_lshl_add_u64 v[42:43], s[8:9], 0, v[32:33]
	s_cbranch_vccz .LBB0_898
	s_mov_b32 s0, 0x3f317217
	s_mov_b32 s2, 0x3d800000
	s_mov_b32 s6, 0x3377d1cf
	s_mov_b32 s98, 1.0
	v_mov_b32_e32 v173, v177
	v_pk_add_f32 v[28:29], v[28:29], v[218:219]
	v_pk_add_f32 v[30:31], v[30:31], v[220:221]
	v_pk_add_f32 v[24:25], v[24:25], v[214:215]
	v_pk_add_f32 v[26:27], v[26:27], v[216:217]
	v_min_f32_e32 v230, 0, v28
	v_min_f32_e32 v231, 0, v29
	v_min_f32_e32 v232, 0, v30
	v_min_f32_e32 v233, 0, v31
	v_min_f32_e32 v234, 0, v24
	v_min_f32_e32 v235, 0, v25
	v_min_f32_e32 v236, 0, v26
	v_min_f32_e32 v237, 0, v27
	v_mul_f32_e64 v28, |v28|, s70
	v_mul_f32_e64 v29, |v29|, s70
	v_mul_f32_e64 v30, |v30|, s70
	v_mul_f32_e64 v31, |v31|, s70
	v_mul_f32_e64 v24, |v24|, s70
	v_mul_f32_e64 v25, |v25|, s70
	v_mul_f32_e64 v26, |v26|, s70
	v_mul_f32_e64 v27, |v27|, s70
	v_exp_f32_e32 v28, v28
	v_exp_f32_e32 v29, v29
	v_exp_f32_e32 v30, v30
	v_exp_f32_e32 v31, v31
	v_exp_f32_e32 v24, v24
	v_exp_f32_e32 v25, v25
	v_exp_f32_e32 v26, v26
	v_exp_f32_e32 v27, v27
	v_pk_add_f32 v[28:29], v[28:29], s[98:99] op_sel_hi:[1,0]
	v_pk_add_f32 v[30:31], v[30:31], s[98:99] op_sel_hi:[1,0]
	v_pk_add_f32 v[24:25], v[24:25], s[98:99] op_sel_hi:[1,0]
	v_pk_add_f32 v[26:27], v[26:27], s[98:99] op_sel_hi:[1,0]
	v_log_f32_e32 v28, v28
	v_log_f32_e32 v29, v29
	v_log_f32_e32 v30, v30
	v_log_f32_e32 v31, v31
	v_log_f32_e32 v24, v24
	v_log_f32_e32 v25, v25
	v_log_f32_e32 v26, v26
	v_log_f32_e32 v27, v27
	v_lshl_add_u64 v[32:33], v[42:43], 0, v[172:173]
	v_pk_mul_f32 v[238:239], v[28:29], s[0:1] op_sel_hi:[1,0]
	v_pk_mul_f32 v[240:241], v[30:31], s[0:1] op_sel_hi:[1,0]
	v_pk_mul_f32 v[242:243], v[24:25], s[0:1] op_sel_hi:[1,0]
	v_pk_mul_f32 v[244:245], v[26:27], s[0:1] op_sel_hi:[1,0]
	v_pk_fma_f32 v[238:239], v[28:29], s[0:1], v[238:239] op_sel_hi:[1,0,1] neg_lo:[0,0,1] neg_hi:[0,0,1]
	v_pk_fma_f32 v[240:241], v[30:31], s[0:1], v[240:241] op_sel_hi:[1,0,1] neg_lo:[0,0,1] neg_hi:[0,0,1]
	v_pk_fma_f32 v[242:243], v[24:25], s[0:1], v[242:243] op_sel_hi:[1,0,1] neg_lo:[0,0,1] neg_hi:[0,0,1]
	v_pk_fma_f32 v[244:245], v[26:27], s[0:1], v[244:245] op_sel_hi:[1,0,1] neg_lo:[0,0,1] neg_hi:[0,0,1]
	v_pk_fma_f32 v[238:239], v[28:29], s[6:7], v[238:239] op_sel_hi:[1,0,1]
	v_pk_fma_f32 v[240:241], v[30:31], s[6:7], v[240:241] op_sel_hi:[1,0,1]
	v_pk_fma_f32 v[242:243], v[24:25], s[6:7], v[242:243] op_sel_hi:[1,0,1]
	v_pk_fma_f32 v[244:245], v[26:27], s[6:7], v[244:245] op_sel_hi:[1,0,1]
	v_pk_fma_f32 v[238:239], v[28:29], s[0:1], v[238:239] op_sel_hi:[1,0,1]
	v_pk_fma_f32 v[240:241], v[30:31], s[0:1], v[240:241] op_sel_hi:[1,0,1]
	v_pk_fma_f32 v[242:243], v[24:25], s[0:1], v[242:243] op_sel_hi:[1,0,1]
	v_pk_fma_f32 v[244:245], v[26:27], s[0:1], v[244:245] op_sel_hi:[1,0,1]
	v_pk_add_f32 v[28:29], v[230:231], v[238:239] neg_lo:[0,1] neg_hi:[0,1]
	v_pk_add_f32 v[30:31], v[232:233], v[240:241] neg_lo:[0,1] neg_hi:[0,1]
	v_pk_add_f32 v[24:25], v[234:235], v[242:243] neg_lo:[0,1] neg_hi:[0,1]
	v_pk_add_f32 v[26:27], v[236:237], v[244:245] neg_lo:[0,1] neg_hi:[0,1]
	v_pk_mul_f32 v[28:29], v[28:29], s[2:3] op_sel_hi:[1,0]
	v_pk_mul_f32 v[30:31], v[30:31], s[2:3] op_sel_hi:[1,0]
	v_pk_mul_f32 v[24:25], v[24:25], s[2:3] op_sel_hi:[1,0]
	v_pk_mul_f32 v[26:27], v[26:27], s[2:3] op_sel_hi:[1,0]
	s_mov_b32 s0, 0x7f800000
	s_mov_b64 s[6:7], exec
	s_mov_b64 vcc, 0
	global_store_dwordx4 v[32:33], v[28:31], off
	global_store_dwordx4 v[32:33], v[24:27], off offset:16

.LBB0_911:
	s_and_b64 vcc, exec, s[0:1]
	s_cbranch_vccz .LBB0_913
	s_mov_b32 s0, 0x3f317217
	s_mov_b32 s2, 0x3d800000
	s_mov_b32 s6, 0x3377d1cf
	s_mov_b32 s98, 1.0
	v_mov_b32_e32 v173, v177
	v_pk_add_f32 v[20:21], v[20:21], v[226:227]
	v_pk_add_f32 v[22:23], v[22:23], v[228:229]
	v_pk_add_f32 v[16:17], v[16:17], v[222:223]
	v_pk_add_f32 v[18:19], v[18:19], v[224:225]
	v_min_f32_e32 v230, 0, v20
	v_min_f32_e32 v231, 0, v21
	v_min_f32_e32 v232, 0, v22
	v_min_f32_e32 v233, 0, v23
	v_min_f32_e32 v234, 0, v16
	v_min_f32_e32 v235, 0, v17
	v_min_f32_e32 v236, 0, v18
	v_min_f32_e32 v237, 0, v19
	v_mul_f32_e64 v20, |v20|, s70
	v_mul_f32_e64 v21, |v21|, s70
	v_mul_f32_e64 v22, |v22|, s70
	v_mul_f32_e64 v23, |v23|, s70
	v_mul_f32_e64 v16, |v16|, s70
	v_mul_f32_e64 v17, |v17|, s70
	v_mul_f32_e64 v18, |v18|, s70
	v_mul_f32_e64 v19, |v19|, s70
	v_exp_f32_e32 v20, v20
	v_exp_f32_e32 v21, v21
	v_exp_f32_e32 v22, v22
	v_exp_f32_e32 v23, v23
	v_exp_f32_e32 v16, v16
	v_exp_f32_e32 v17, v17
	v_exp_f32_e32 v18, v18
	v_exp_f32_e32 v19, v19
	v_pk_add_f32 v[20:21], v[20:21], s[98:99] op_sel_hi:[1,0]
	v_pk_add_f32 v[22:23], v[22:23], s[98:99] op_sel_hi:[1,0]
	v_pk_add_f32 v[16:17], v[16:17], s[98:99] op_sel_hi:[1,0]
	v_pk_add_f32 v[18:19], v[18:19], s[98:99] op_sel_hi:[1,0]
	v_log_f32_e32 v20, v20
	v_log_f32_e32 v21, v21
	v_log_f32_e32 v22, v22
	v_log_f32_e32 v23, v23
	v_log_f32_e32 v16, v16
	v_log_f32_e32 v17, v17
	v_log_f32_e32 v18, v18
	v_log_f32_e32 v19, v19
	v_lshl_add_u64 v[24:25], v[42:43], 0, v[172:173]
	v_pk_mul_f32 v[238:239], v[20:21], s[0:1] op_sel_hi:[1,0]
	v_pk_mul_f32 v[240:241], v[22:23], s[0:1] op_sel_hi:[1,0]
	v_pk_mul_f32 v[242:243], v[16:17], s[0:1] op_sel_hi:[1,0]
	v_pk_mul_f32 v[244:245], v[18:19], s[0:1] op_sel_hi:[1,0]
	v_pk_fma_f32 v[238:239], v[20:21], s[0:1], v[238:239] op_sel_hi:[1,0,1] neg_lo:[0,0,1] neg_hi:[0,0,1]
	v_pk_fma_f32 v[240:241], v[22:23], s[0:1], v[240:241] op_sel_hi:[1,0,1] neg_lo:[0,0,1] neg_hi:[0,0,1]
	v_pk_fma_f32 v[242:243], v[16:17], s[0:1], v[242:243] op_sel_hi:[1,0,1] neg_lo:[0,0,1] neg_hi:[0,0,1]
	v_pk_fma_f32 v[244:245], v[18:19], s[0:1], v[244:245] op_sel_hi:[1,0,1] neg_lo:[0,0,1] neg_hi:[0,0,1]
	v_pk_fma_f32 v[238:239], v[20:21], s[6:7], v[238:239] op_sel_hi:[1,0,1]
	v_pk_fma_f32 v[240:241], v[22:23], s[6:7], v[240:241] op_sel_hi:[1,0,1]
	v_pk_fma_f32 v[242:243], v[16:17], s[6:7], v[242:243] op_sel_hi:[1,0,1]
	v_pk_fma_f32 v[244:245], v[18:19], s[6:7], v[244:245] op_sel_hi:[1,0,1]
	v_pk_fma_f32 v[238:239], v[20:21], s[0:1], v[238:239] op_sel_hi:[1,0,1]
	v_pk_fma_f32 v[240:241], v[22:23], s[0:1], v[240:241] op_sel_hi:[1,0,1]
	v_pk_fma_f32 v[242:243], v[16:17], s[0:1], v[242:243] op_sel_hi:[1,0,1]
	v_pk_fma_f32 v[244:245], v[18:19], s[0:1], v[244:245] op_sel_hi:[1,0,1]
	v_pk_add_f32 v[20:21], v[230:231], v[238:239] neg_lo:[0,1] neg_hi:[0,1]
	v_pk_add_f32 v[22:23], v[232:233], v[240:241] neg_lo:[0,1] neg_hi:[0,1]
	v_pk_add_f32 v[16:17], v[234:235], v[242:243] neg_lo:[0,1] neg_hi:[0,1]
	v_pk_add_f32 v[18:19], v[236:237], v[244:245] neg_lo:[0,1] neg_hi:[0,1]
	v_pk_mul_f32 v[20:21], v[20:21], s[2:3] op_sel_hi:[1,0]
	v_pk_mul_f32 v[22:23], v[22:23], s[2:3] op_sel_hi:[1,0]
	v_pk_mul_f32 v[16:17], v[16:17], s[2:3] op_sel_hi:[1,0]
	v_pk_mul_f32 v[18:19], v[18:19], s[2:3] op_sel_hi:[1,0]
	s_mov_b32 s0, 0x7f800000
	s_mov_b64 s[6:7], exec
	s_mov_b64 vcc, 0
	global_store_dwordx4 v[24:25], v[20:23], off offset:512
	global_store_dwordx4 v[24:25], v[16:19], off offset:528

.LBB0_936:
	s_nop 1
	v_lshlrev_b64 v[16:17], 10, v[24:25]
	s_and_b64 vcc, exec, s[0:1]
	v_lshl_add_u64 v[24:25], s[8:9], 0, v[16:17]
	s_cbranch_vccz .LBB0_938
	s_mov_b32 s0, 0x3f317217
	s_mov_b32 s2, 0x3d800000
	s_mov_b32 s6, 0x3377d1cf
	s_mov_b32 s98, 1.0
	v_mov_b32_e32 v173, v177
	v_pk_add_f32 v[12:13], v[12:13], v[218:219]
	v_pk_add_f32 v[14:15], v[14:15], v[220:221]
	v_pk_add_f32 v[8:9], v[8:9], v[214:215]
	v_pk_add_f32 v[10:11], v[10:11], v[216:217]
	v_min_f32_e32 v230, 0, v12
	v_min_f32_e32 v231, 0, v13
	v_min_f32_e32 v232, 0, v14
	v_min_f32_e32 v233, 0, v15
	v_min_f32_e32 v234, 0, v8
	v_min_f32_e32 v235, 0, v9
	v_min_f32_e32 v236, 0, v10
	v_min_f32_e32 v237, 0, v11
	v_mul_f32_e64 v12, |v12|, s70
	v_mul_f32_e64 v13, |v13|, s70
	v_mul_f32_e64 v14, |v14|, s70
	v_mul_f32_e64 v15, |v15|, s70
	v_mul_f32_e64 v8, |v8|, s70
	v_mul_f32_e64 v9, |v9|, s70
	v_mul_f32_e64 v10, |v10|, s70
	v_mul_f32_e64 v11, |v11|, s70
	v_exp_f32_e32 v12, v12
	v_exp_f32_e32 v13, v13
	v_exp_f32_e32 v14, v14
	v_exp_f32_e32 v15, v15
	v_exp_f32_e32 v8, v8
	v_exp_f32_e32 v9, v9
	v_exp_f32_e32 v10, v10
	v_exp_f32_e32 v11, v11
	v_pk_add_f32 v[12:13], v[12:13], s[98:99] op_sel_hi:[1,0]
	v_pk_add_f32 v[14:15], v[14:15], s[98:99] op_sel_hi:[1,0]
	v_pk_add_f32 v[8:9], v[8:9], s[98:99] op_sel_hi:[1,0]
	v_pk_add_f32 v[10:11], v[10:11], s[98:99] op_sel_hi:[1,0]
	v_log_f32_e32 v12, v12
	v_log_f32_e32 v13, v13
	v_log_f32_e32 v14, v14
	v_log_f32_e32 v15, v15
	v_log_f32_e32 v8, v8
	v_log_f32_e32 v9, v9
	v_log_f32_e32 v10, v10
	v_log_f32_e32 v11, v11
	v_lshl_add_u64 v[16:17], v[24:25], 0, v[172:173]
	v_pk_mul_f32 v[238:239], v[12:13], s[0:1] op_sel_hi:[1,0]
	v_pk_mul_f32 v[240:241], v[14:15], s[0:1] op_sel_hi:[1,0]
	v_pk_mul_f32 v[242:243], v[8:9], s[0:1] op_sel_hi:[1,0]
	v_pk_mul_f32 v[244:245], v[10:11], s[0:1] op_sel_hi:[1,0]
	v_pk_fma_f32 v[238:239], v[12:13], s[0:1], v[238:239] op_sel_hi:[1,0,1] neg_lo:[0,0,1] neg_hi:[0,0,1]
	v_pk_fma_f32 v[240:241], v[14:15], s[0:1], v[240:241] op_sel_hi:[1,0,1] neg_lo:[0,0,1] neg_hi:[0,0,1]
	v_pk_fma_f32 v[242:243], v[8:9], s[0:1], v[242:243] op_sel_hi:[1,0,1] neg_lo:[0,0,1] neg_hi:[0,0,1]
	v_pk_fma_f32 v[244:245], v[10:11], s[0:1], v[244:245] op_sel_hi:[1,0,1] neg_lo:[0,0,1] neg_hi:[0,0,1]
	v_pk_fma_f32 v[238:239], v[12:13], s[6:7], v[238:239] op_sel_hi:[1,0,1]
	v_pk_fma_f32 v[240:241], v[14:15], s[6:7], v[240:241] op_sel_hi:[1,0,1]
	v_pk_fma_f32 v[242:243], v[8:9], s[6:7], v[242:243] op_sel_hi:[1,0,1]
	v_pk_fma_f32 v[244:245], v[10:11], s[6:7], v[244:245] op_sel_hi:[1,0,1]
	v_pk_fma_f32 v[238:239], v[12:13], s[0:1], v[238:239] op_sel_hi:[1,0,1]
	v_pk_fma_f32 v[240:241], v[14:15], s[0:1], v[240:241] op_sel_hi:[1,0,1]
	v_pk_fma_f32 v[242:243], v[8:9], s[0:1], v[242:243] op_sel_hi:[1,0,1]
	v_pk_fma_f32 v[244:245], v[10:11], s[0:1], v[244:245] op_sel_hi:[1,0,1]
	v_pk_add_f32 v[12:13], v[230:231], v[238:239] neg_lo:[0,1] neg_hi:[0,1]
	v_pk_add_f32 v[14:15], v[232:233], v[240:241] neg_lo:[0,1] neg_hi:[0,1]
	v_pk_add_f32 v[8:9], v[234:235], v[242:243] neg_lo:[0,1] neg_hi:[0,1]
	v_pk_add_f32 v[10:11], v[236:237], v[244:245] neg_lo:[0,1] neg_hi:[0,1]
	v_pk_mul_f32 v[12:13], v[12:13], s[2:3] op_sel_hi:[1,0]
	v_pk_mul_f32 v[14:15], v[14:15], s[2:3] op_sel_hi:[1,0]
	v_pk_mul_f32 v[8:9], v[8:9], s[2:3] op_sel_hi:[1,0]
	v_pk_mul_f32 v[10:11], v[10:11], s[2:3] op_sel_hi:[1,0]
	s_mov_b32 s0, 0x7f800000
	s_mov_b64 s[6:7], exec
	s_mov_b64 vcc, 0
	global_store_dwordx4 v[16:17], v[12:15], off
	global_store_dwordx4 v[16:17], v[8:11], off offset:16

.LBB0_951:
	s_and_b64 vcc, exec, s[0:1]
	s_cbranch_vccz .LBB0_958
	s_mov_b32 s0, 0x3f317217
	s_mov_b32 s2, 0x3d800000
	s_mov_b32 s6, 0x3377d1cf
	s_mov_b32 s98, 1.0
	v_mov_b32_e32 v173, v177
	v_pk_add_f32 v[4:5], v[4:5], v[226:227]
	v_pk_add_f32 v[6:7], v[6:7], v[228:229]
	v_pk_add_f32 v[0:1], v[0:1], v[222:223]
	v_pk_add_f32 v[2:3], v[2:3], v[224:225]
	v_min_f32_e32 v230, 0, v4
	v_min_f32_e32 v231, 0, v5
	v_min_f32_e32 v232, 0, v6
	v_min_f32_e32 v233, 0, v7
	v_min_f32_e32 v234, 0, v0
	v_min_f32_e32 v235, 0, v1
	v_min_f32_e32 v236, 0, v2
	v_min_f32_e32 v237, 0, v3
	v_mul_f32_e64 v4, |v4|, s70
	v_mul_f32_e64 v5, |v5|, s70
	v_mul_f32_e64 v6, |v6|, s70
	v_mul_f32_e64 v7, |v7|, s70
	v_mul_f32_e64 v0, |v0|, s70
	v_mul_f32_e64 v1, |v1|, s70
	v_mul_f32_e64 v2, |v2|, s70
	v_mul_f32_e64 v3, |v3|, s70
	v_exp_f32_e32 v4, v4
	v_exp_f32_e32 v5, v5
	v_exp_f32_e32 v6, v6
	v_exp_f32_e32 v7, v7
	v_exp_f32_e32 v0, v0
	v_exp_f32_e32 v1, v1
	v_exp_f32_e32 v2, v2
	v_exp_f32_e32 v3, v3
	v_pk_add_f32 v[4:5], v[4:5], s[98:99] op_sel_hi:[1,0]
	v_pk_add_f32 v[6:7], v[6:7], s[98:99] op_sel_hi:[1,0]
	v_pk_add_f32 v[0:1], v[0:1], s[98:99] op_sel_hi:[1,0]
	v_pk_add_f32 v[2:3], v[2:3], s[98:99] op_sel_hi:[1,0]
	v_log_f32_e32 v4, v4
	v_log_f32_e32 v5, v5
	v_log_f32_e32 v6, v6
	v_log_f32_e32 v7, v7
	v_log_f32_e32 v0, v0
	v_log_f32_e32 v1, v1
	v_log_f32_e32 v2, v2
	v_log_f32_e32 v3, v3
	v_lshl_add_u64 v[8:9], v[24:25], 0, v[172:173]
	v_pk_mul_f32 v[238:239], v[4:5], s[0:1] op_sel_hi:[1,0]
	v_pk_mul_f32 v[240:241], v[6:7], s[0:1] op_sel_hi:[1,0]
	v_pk_mul_f32 v[242:243], v[0:1], s[0:1] op_sel_hi:[1,0]
	v_pk_mul_f32 v[244:245], v[2:3], s[0:1] op_sel_hi:[1,0]
	v_pk_fma_f32 v[238:239], v[4:5], s[0:1], v[238:239] op_sel_hi:[1,0,1] neg_lo:[0,0,1] neg_hi:[0,0,1]
	v_pk_fma_f32 v[240:241], v[6:7], s[0:1], v[240:241] op_sel_hi:[1,0,1] neg_lo:[0,0,1] neg_hi:[0,0,1]
	v_pk_fma_f32 v[242:243], v[0:1], s[0:1], v[242:243] op_sel_hi:[1,0,1] neg_lo:[0,0,1] neg_hi:[0,0,1]
	v_pk_fma_f32 v[244:245], v[2:3], s[0:1], v[244:245] op_sel_hi:[1,0,1] neg_lo:[0,0,1] neg_hi:[0,0,1]
	v_pk_fma_f32 v[238:239], v[4:5], s[6:7], v[238:239] op_sel_hi:[1,0,1]
	v_pk_fma_f32 v[240:241], v[6:7], s[6:7], v[240:241] op_sel_hi:[1,0,1]
	v_pk_fma_f32 v[242:243], v[0:1], s[6:7], v[242:243] op_sel_hi:[1,0,1]
	v_pk_fma_f32 v[244:245], v[2:3], s[6:7], v[244:245] op_sel_hi:[1,0,1]
	v_pk_fma_f32 v[238:239], v[4:5], s[0:1], v[238:239] op_sel_hi:[1,0,1]
	v_pk_fma_f32 v[240:241], v[6:7], s[0:1], v[240:241] op_sel_hi:[1,0,1]
	v_pk_fma_f32 v[242:243], v[0:1], s[0:1], v[242:243] op_sel_hi:[1,0,1]
	v_pk_fma_f32 v[244:245], v[2:3], s[0:1], v[244:245] op_sel_hi:[1,0,1]
	v_pk_add_f32 v[4:5], v[230:231], v[238:239] neg_lo:[0,1] neg_hi:[0,1]
	v_pk_add_f32 v[6:7], v[232:233], v[240:241] neg_lo:[0,1] neg_hi:[0,1]
	v_pk_add_f32 v[0:1], v[234:235], v[242:243] neg_lo:[0,1] neg_hi:[0,1]
	v_pk_add_f32 v[2:3], v[236:237], v[244:245] neg_lo:[0,1] neg_hi:[0,1]
	v_pk_mul_f32 v[4:5], v[4:5], s[2:3] op_sel_hi:[1,0]
	v_pk_mul_f32 v[6:7], v[6:7], s[2:3] op_sel_hi:[1,0]
	v_pk_mul_f32 v[0:1], v[0:1], s[2:3] op_sel_hi:[1,0]
	v_pk_mul_f32 v[2:3], v[2:3], s[2:3] op_sel_hi:[1,0]
	s_mov_b32 s0, 0x7f800000
	s_mov_b64 s[6:7], exec
	s_mov_b64 vcc, 0
	global_store_dwordx4 v[8:9], v[4:7], off offset:512
	global_store_dwordx4 v[8:9], v[0:3], off offset:528
	s_andn2_b64 vcc, exec, s[38:39]
	s_mov_b64 s[0:1], -1
	s_cbranch_vccnz .LBB0_615
	s_branch .LBB0_959
